# fp8 GEMM loops: MFMAs of each 8-block reordered so 4 consecutive MFMAs share the weight fragment operand (bit-exact; lower operand toggling)
# baseline (speedup 1.0000x reference)
.LBB0_603:
	v_add_u32_e32 v14, s48, v178
	v_add_u32_e32 v170, s49, v178
	ds_read_b128 v[2:5], v14
	ds_read_b128 v[6:9], v14 offset:1024
	ds_read_b128 v[10:13], v14 offset:2048
	ds_read_b128 v[14:17], v14 offset:3072
	ds_read_b128 v[18:21], v170
	ds_read_b128 v[22:25], v170 offset:1024
	ds_read_b128 v[184:187], v170 offset:2048
	ds_read_b128 v[188:191], v170 offset:3072
	s_add_i32 s69, s24, 2
	s_add_u32 s25, s22, 0xfffc0080
	s_addc_u32 s26, s23, -1
	s_cmp_eq_u32 s13, s24
	s_cselect_b32 s24, s20, s15
	s_cselect_b32 s27, s19, s26
	s_cselect_b32 s26, s18, s25
	s_cselect_b32 s25, s21, s68
	v_lshl_add_u64 v[216:217], s[22:23], 0, v[162:163]
	s_add_i32 m0, s17, 0xc000
	ds_read_b128 v[170:173], v181
	ds_read_b128 v[174:177], v181 offset:1024
	ds_read_b128 v[192:195], v181 offset:2048
	ds_read_b128 v[196:199], v181 offset:3072
	ds_read_b128 v[200:203], v181 offset:4096
	ds_read_b128 v[204:207], v181 offset:5120
	ds_read_b128 v[208:211], v181 offset:6144
	ds_read_b128 v[212:215], v181 offset:7168
	global_load_lds_dwordx4 v[216:217], off
	v_lshl_add_u64 v[216:217], s[22:23], 0, v[164:165]
	s_add_i32 m0, s17, 0xe000
	s_nop 0
	global_load_lds_dwordx4 v[216:217], off
	s_waitcnt vmcnt(8)
	s_waitcnt lgkmcnt(0)
	s_barrier
	s_setprio 1
	s_waitcnt lgkmcnt(0)
	v_mfma_scale_f32_16x16x128_f8f6f4 v[150:153], v[2:9], v[170:177], v[150:153], v182, v182 op_sel_hi:[0,0,0]
	v_mfma_scale_f32_16x16x128_f8f6f4 v[142:145], v[2:9], v[192:199], v[142:145], v182, v182 op_sel_hi:[0,0,0]
	v_mfma_scale_f32_16x16x128_f8f6f4 v[134:137], v[2:9], v[200:207], v[134:137], v182, v182 op_sel_hi:[0,0,0]
	v_mfma_scale_f32_16x16x128_f8f6f4 v[126:129], v[2:9], v[208:215], v[126:129], v182, v182 op_sel_hi:[0,0,0]
	v_mfma_scale_f32_16x16x128_f8f6f4 v[146:149], v[10:17], v[170:177], v[146:149], v182, v182 op_sel_hi:[0,0,0]
	v_mfma_scale_f32_16x16x128_f8f6f4 v[138:141], v[10:17], v[192:199], v[138:141], v182, v182 op_sel_hi:[0,0,0]
	v_mfma_scale_f32_16x16x128_f8f6f4 v[130:133], v[10:17], v[200:207], v[130:133], v182, v182 op_sel_hi:[0,0,0]
	v_mfma_scale_f32_16x16x128_f8f6f4 v[122:125], v[10:17], v[208:215], v[122:125], v182, v182 op_sel_hi:[0,0,0]
	s_setprio 0
	s_setprio 1
	v_mfma_scale_f32_16x16x128_f8f6f4 v[118:121], v[18:25], v[170:177], v[118:121], v182, v182 op_sel_hi:[0,0,0]
	v_mfma_scale_f32_16x16x128_f8f6f4 v[110:113], v[18:25], v[192:199], v[110:113], v182, v182 op_sel_hi:[0,0,0]
	v_mfma_scale_f32_16x16x128_f8f6f4 v[102:105], v[18:25], v[200:207], v[102:105], v182, v182 op_sel_hi:[0,0,0]
	v_mfma_scale_f32_16x16x128_f8f6f4 v[94:97], v[18:25], v[208:215], v[94:97], v182, v182 op_sel_hi:[0,0,0]
	v_mfma_scale_f32_16x16x128_f8f6f4 v[114:117], v[184:191], v[170:177], v[114:117], v182, v182 op_sel_hi:[0,0,0]
	v_mfma_scale_f32_16x16x128_f8f6f4 v[106:109], v[184:191], v[192:199], v[106:109], v182, v182 op_sel_hi:[0,0,0]
	v_mfma_scale_f32_16x16x128_f8f6f4 v[98:101], v[184:191], v[200:207], v[98:101], v182, v182 op_sel_hi:[0,0,0]
	v_mfma_scale_f32_16x16x128_f8f6f4 v[90:93], v[184:191], v[208:215], v[90:93], v182, v182 op_sel_hi:[0,0,0]
	s_setprio 0
	s_barrier
	s_add_i32 s50, s48, s29
	v_lshl_add_u64 v[170:171], s[24:25], 0, v[156:157]
	s_mov_b32 m0, s50
	ds_read_b128 v[192:195], v181 offset:16384
	ds_read_b128 v[196:199], v181 offset:17408
	ds_read_b128 v[200:203], v181 offset:18432
	ds_read_b128 v[204:207], v181 offset:19456
	ds_read_b128 v[208:211], v181 offset:20480
	ds_read_b128 v[212:215], v181 offset:21504
	ds_read_b128 v[216:219], v181 offset:22528
	ds_read_b128 v[220:223], v181 offset:23552
	global_load_lds_dwordx4 v[170:171], off
	s_add_i32 m0, s50, 0x2000
	s_add_u32 s70, s24, 0x40000
	v_lshl_add_u64 v[172:173], s[24:25], 0, v[160:161]
	s_addc_u32 s71, s25, 0
	s_add_i32 s50, s49, s29
	global_load_lds_dwordx4 v[172:173], off
	v_lshl_add_u64 v[174:175], s[70:71], 0, v[156:157]
	s_mov_b32 m0, s50
	v_lshl_add_u64 v[176:177], s[26:27], 0, v[158:159]
	global_load_lds_dwordx4 v[174:175], off
	v_lshl_add_u64 v[174:175], s[70:71], 0, v[160:161]
	s_add_i32 m0, s50, 0x2000
	s_nop 0
	global_load_lds_dwordx4 v[174:175], off
	v_lshl_add_u64 v[174:175], s[26:27], 0, v[154:155]
	s_mov_b32 m0, s17
	s_nop 0
	global_load_lds_dwordx4 v[174:175], off
	s_mov_b32 m0, s39
	s_nop 0
	global_load_lds_dwordx4 v[176:177], off
	s_waitcnt vmcnt(8)
	s_waitcnt lgkmcnt(0)
	s_barrier
	s_setprio 1
	s_waitcnt lgkmcnt(0)
	v_mfma_scale_f32_16x16x128_f8f6f4 v[86:89], v[2:9], v[192:199], v[86:89], v182, v182 op_sel_hi:[0,0,0]
	v_mfma_scale_f32_16x16x128_f8f6f4 v[78:81], v[2:9], v[200:207], v[78:81], v182, v182 op_sel_hi:[0,0,0]
	v_mfma_scale_f32_16x16x128_f8f6f4 v[70:73], v[2:9], v[208:215], v[70:73], v182, v182 op_sel_hi:[0,0,0]
	v_mfma_scale_f32_16x16x128_f8f6f4 v[62:65], v[2:9], v[216:223], v[62:65], v182, v182 op_sel_hi:[0,0,0]
	v_mfma_scale_f32_16x16x128_f8f6f4 v[82:85], v[10:17], v[192:199], v[82:85], v182, v182 op_sel_hi:[0,0,0]
	v_mfma_scale_f32_16x16x128_f8f6f4 v[74:77], v[10:17], v[200:207], v[74:77], v182, v182 op_sel_hi:[0,0,0]
	v_mfma_scale_f32_16x16x128_f8f6f4 v[66:69], v[10:17], v[208:215], v[66:69], v182, v182 op_sel_hi:[0,0,0]
	v_mfma_scale_f32_16x16x128_f8f6f4 v[58:61], v[10:17], v[216:223], v[58:61], v182, v182 op_sel_hi:[0,0,0]
	s_setprio 0
	s_setprio 1
	v_mfma_scale_f32_16x16x128_f8f6f4 v[54:57], v[18:25], v[192:199], v[54:57], v182, v182 op_sel_hi:[0,0,0]
	v_mfma_scale_f32_16x16x128_f8f6f4 v[46:49], v[18:25], v[200:207], v[46:49], v182, v182 op_sel_hi:[0,0,0]
	v_mfma_scale_f32_16x16x128_f8f6f4 v[38:41], v[18:25], v[208:215], v[38:41], v182, v182 op_sel_hi:[0,0,0]
	v_mfma_scale_f32_16x16x128_f8f6f4 v[30:33], v[18:25], v[216:223], v[30:33], v182, v182 op_sel_hi:[0,0,0]
	v_mfma_scale_f32_16x16x128_f8f6f4 v[50:53], v[184:191], v[192:199], v[50:53], v182, v182 op_sel_hi:[0,0,0]
	v_mfma_scale_f32_16x16x128_f8f6f4 v[42:45], v[184:191], v[200:207], v[42:45], v182, v182 op_sel_hi:[0,0,0]
	v_mfma_scale_f32_16x16x128_f8f6f4 v[34:37], v[184:191], v[208:215], v[34:37], v182, v182 op_sel_hi:[0,0,0]
	v_mfma_scale_f32_16x16x128_f8f6f4 v[26:29], v[184:191], v[216:223], v[26:29], v182, v182 op_sel_hi:[0,0,0]
	s_setprio 0
	s_barrier
	s_add_i32 s70, 0, 0x18000
	s_add_i32 s50, 0, 0x1c000
	v_add_u32_e32 v2, s70, v178
	v_add_u32_e32 v22, s50, v178
	ds_read_b128 v[10:13], v2
	ds_read_b128 v[14:17], v2 offset:1024
	ds_read_b128 v[184:187], v2 offset:2048
	ds_read_b128 v[188:191], v2 offset:3072
	ds_read_b128 v[2:5], v22
	ds_read_b128 v[6:9], v22 offset:1024
	ds_read_b128 v[18:21], v22 offset:2048
	ds_read_b128 v[22:25], v22 offset:3072
	s_add_u32 s26, s26, 0x40000
	s_addc_u32 s27, s27, 0
	s_mov_b32 m0, s40
	v_lshl_add_u64 v[224:225], s[26:27], 0, v[154:155]
	ds_read_b128 v[192:195], v181 offset:32768
	ds_read_b128 v[196:199], v181 offset:33792
	ds_read_b128 v[200:203], v181 offset:34816
	ds_read_b128 v[204:207], v181 offset:35840
	ds_read_b128 v[208:211], v181 offset:36864
	ds_read_b128 v[212:215], v181 offset:37888
	ds_read_b128 v[216:219], v181 offset:38912
	ds_read_b128 v[220:223], v181 offset:39936
	global_load_lds_dwordx4 v[224:225], off
	v_lshl_add_u64 v[224:225], s[26:27], 0, v[158:159]
	s_mov_b32 m0, s41
	s_nop 0
	global_load_lds_dwordx4 v[224:225], off
	s_waitcnt vmcnt(8)
	s_waitcnt lgkmcnt(0)
	s_barrier
	s_setprio 1
	s_waitcnt lgkmcnt(0)
	v_mfma_scale_f32_16x16x128_f8f6f4 v[150:153], v[10:17], v[192:199], v[150:153], v182, v182 op_sel_hi:[0,0,0]
	v_mfma_scale_f32_16x16x128_f8f6f4 v[142:145], v[10:17], v[200:207], v[142:145], v182, v182 op_sel_hi:[0,0,0]
	v_mfma_scale_f32_16x16x128_f8f6f4 v[134:137], v[10:17], v[208:215], v[134:137], v182, v182 op_sel_hi:[0,0,0]
	v_mfma_scale_f32_16x16x128_f8f6f4 v[126:129], v[10:17], v[216:223], v[126:129], v182, v182 op_sel_hi:[0,0,0]
	v_mfma_scale_f32_16x16x128_f8f6f4 v[146:149], v[184:191], v[192:199], v[146:149], v182, v182 op_sel_hi:[0,0,0]
	v_mfma_scale_f32_16x16x128_f8f6f4 v[138:141], v[184:191], v[200:207], v[138:141], v182, v182 op_sel_hi:[0,0,0]
	v_mfma_scale_f32_16x16x128_f8f6f4 v[130:133], v[184:191], v[208:215], v[130:133], v182, v182 op_sel_hi:[0,0,0]
	v_mfma_scale_f32_16x16x128_f8f6f4 v[122:125], v[184:191], v[216:223], v[122:125], v182, v182 op_sel_hi:[0,0,0]
	s_setprio 0
	s_setprio 1
	v_mfma_scale_f32_16x16x128_f8f6f4 v[118:121], v[2:9], v[192:199], v[118:121], v182, v182 op_sel_hi:[0,0,0]
	v_mfma_scale_f32_16x16x128_f8f6f4 v[110:113], v[2:9], v[200:207], v[110:113], v182, v182 op_sel_hi:[0,0,0]
	v_mfma_scale_f32_16x16x128_f8f6f4 v[102:105], v[2:9], v[208:215], v[102:105], v182, v182 op_sel_hi:[0,0,0]
	v_mfma_scale_f32_16x16x128_f8f6f4 v[94:97], v[2:9], v[216:223], v[94:97], v182, v182 op_sel_hi:[0,0,0]
	v_mfma_scale_f32_16x16x128_f8f6f4 v[114:117], v[18:25], v[192:199], v[114:117], v182, v182 op_sel_hi:[0,0,0]
	v_mfma_scale_f32_16x16x128_f8f6f4 v[106:109], v[18:25], v[200:207], v[106:109], v182, v182 op_sel_hi:[0,0,0]
	v_mfma_scale_f32_16x16x128_f8f6f4 v[98:101], v[18:25], v[208:215], v[98:101], v182, v182 op_sel_hi:[0,0,0]
	v_mfma_scale_f32_16x16x128_f8f6f4 v[90:93], v[18:25], v[216:223], v[90:93], v182, v182 op_sel_hi:[0,0,0]
	s_setprio 0
	s_barrier
	s_add_i32 s26, s70, s29
	v_lshl_add_u64 v[170:171], v[170:171], 0, s[8:9]
	s_mov_b32 m0, s26
	ds_read_b128 v[192:195], v181 offset:49152
	ds_read_b128 v[196:199], v181 offset:50176
	ds_read_b128 v[200:203], v181 offset:51200
	ds_read_b128 v[204:207], v181 offset:52224
	ds_read_b128 v[208:211], v181 offset:53248
	ds_read_b128 v[212:215], v181 offset:54272
	ds_read_b128 v[216:219], v181 offset:55296
	ds_read_b128 v[220:223], v181 offset:56320
	global_load_lds_dwordx4 v[170:171], off
	s_add_i32 m0, s26, 0x2000
	s_add_u32 s24, s24, 0x40080
	v_lshl_add_u64 v[170:171], v[172:173], 0, s[8:9]
	s_addc_u32 s25, s25, 0
	s_add_i32 s26, s50, s29
	global_load_lds_dwordx4 v[170:171], off
	v_lshl_add_u64 v[170:171], s[24:25], 0, v[156:157]
	s_mov_b32 m0, s26
	s_nop 0
	global_load_lds_dwordx4 v[170:171], off
	v_lshl_add_u64 v[170:171], s[24:25], 0, v[160:161]
	s_add_i32 m0, s26, 0x2000
	s_nop 0
	global_load_lds_dwordx4 v[170:171], off
	v_lshl_add_u64 v[170:171], v[174:175], 0, s[8:9]
	s_mov_b32 m0, s43
	s_nop 0
	global_load_lds_dwordx4 v[170:171], off
	v_lshl_add_u64 v[170:171], v[176:177], 0, s[8:9]
	s_mov_b32 m0, s44
	s_nop 0
	global_load_lds_dwordx4 v[170:171], off
	s_waitcnt vmcnt(8)
	s_waitcnt lgkmcnt(0)
	s_barrier
	s_setprio 1
	s_waitcnt lgkmcnt(0)
	v_mfma_scale_f32_16x16x128_f8f6f4 v[86:89], v[10:17], v[192:199], v[86:89], v182, v182 op_sel_hi:[0,0,0]
	v_mfma_scale_f32_16x16x128_f8f6f4 v[78:81], v[10:17], v[200:207], v[78:81], v182, v182 op_sel_hi:[0,0,0]
	v_mfma_scale_f32_16x16x128_f8f6f4 v[70:73], v[10:17], v[208:215], v[70:73], v182, v182 op_sel_hi:[0,0,0]
	v_mfma_scale_f32_16x16x128_f8f6f4 v[62:65], v[10:17], v[216:223], v[62:65], v182, v182 op_sel_hi:[0,0,0]
	v_mfma_scale_f32_16x16x128_f8f6f4 v[82:85], v[184:191], v[192:199], v[82:85], v182, v182 op_sel_hi:[0,0,0]
	v_mfma_scale_f32_16x16x128_f8f6f4 v[74:77], v[184:191], v[200:207], v[74:77], v182, v182 op_sel_hi:[0,0,0]
	v_mfma_scale_f32_16x16x128_f8f6f4 v[66:69], v[184:191], v[208:215], v[66:69], v182, v182 op_sel_hi:[0,0,0]
	v_mfma_scale_f32_16x16x128_f8f6f4 v[58:61], v[184:191], v[216:223], v[58:61], v182, v182 op_sel_hi:[0,0,0]
	s_setprio 0
	s_setprio 1
	v_mfma_scale_f32_16x16x128_f8f6f4 v[54:57], v[2:9], v[192:199], v[54:57], v182, v182 op_sel_hi:[0,0,0]
	v_mfma_scale_f32_16x16x128_f8f6f4 v[46:49], v[2:9], v[200:207], v[46:49], v182, v182 op_sel_hi:[0,0,0]
	v_mfma_scale_f32_16x16x128_f8f6f4 v[38:41], v[2:9], v[208:215], v[38:41], v182, v182 op_sel_hi:[0,0,0]
	v_mfma_scale_f32_16x16x128_f8f6f4 v[30:33], v[2:9], v[216:223], v[30:33], v182, v182 op_sel_hi:[0,0,0]
	v_mfma_scale_f32_16x16x128_f8f6f4 v[50:53], v[18:25], v[192:199], v[50:53], v182, v182 op_sel_hi:[0,0,0]
	v_mfma_scale_f32_16x16x128_f8f6f4 v[42:45], v[18:25], v[200:207], v[42:45], v182, v182 op_sel_hi:[0,0,0]
	v_mfma_scale_f32_16x16x128_f8f6f4 v[34:37], v[18:25], v[208:215], v[34:37], v182, v182 op_sel_hi:[0,0,0]
	v_mfma_scale_f32_16x16x128_f8f6f4 v[26:29], v[18:25], v[216:223], v[26:29], v182, v182 op_sel_hi:[0,0,0]
	s_setprio 0
	s_barrier
	s_add_u32 s22, s22, 0x100
	s_addc_u32 s23, s23, 0
	s_add_u32 s15, s15, 0x100
	s_addc_u32 s68, s68, 0
	s_cmp_ge_i32 s69, s62
	s_mov_b32 s24, s69
	s_cbranch_scc0 .LBB0_603

.LBB0_739:
	v_add_u32_e32 v14, s46, v180
	v_add_u32_e32 v172, s47, v180
	ds_read_b128 v[2:5], v14
	ds_read_b128 v[6:9], v14 offset:1024
	ds_read_b128 v[10:13], v14 offset:2048
	ds_read_b128 v[14:17], v14 offset:3072
	ds_read_b128 v[18:21], v172
	ds_read_b128 v[22:25], v172 offset:1024
	ds_read_b128 v[184:187], v172 offset:2048
	ds_read_b128 v[188:191], v172 offset:3072
	s_add_u32 s24, s22, 0xfffc0080
	s_addc_u32 s25, s23, -1
	s_cmp_eq_u32 s62, 12
	s_cselect_b32 s27, s15, s25
	s_cselect_b32 s26, s58, s24
	s_cselect_b32 s25, s13, s61
	s_cselect_b32 s24, s59, s60
	v_lshl_add_u64 v[216:217], s[22:23], 0, v[164:165]
	s_add_i32 m0, s21, 0xc000
	ds_read_b128 v[172:175], v181
	ds_read_b128 v[176:179], v181 offset:1024
	ds_read_b128 v[192:195], v181 offset:2048
	ds_read_b128 v[196:199], v181 offset:3072
	ds_read_b128 v[200:203], v181 offset:4096
	ds_read_b128 v[204:207], v181 offset:5120
	ds_read_b128 v[208:211], v181 offset:6144
	ds_read_b128 v[212:215], v181 offset:7168
	global_load_lds_dwordx4 v[216:217], off
	v_lshl_add_u64 v[216:217], s[22:23], 0, v[166:167]
	s_add_i32 m0, s21, 0xe000
	s_nop 0
	global_load_lds_dwordx4 v[216:217], off
	s_waitcnt vmcnt(8)
	s_waitcnt lgkmcnt(0)
	s_barrier
	s_setprio 1
	s_waitcnt lgkmcnt(0)
	v_mfma_scale_f32_16x16x128_f8f6f4 v[150:153], v[2:9], v[172:179], v[150:153], v182, v182 op_sel_hi:[0,0,0]
	v_mfma_scale_f32_16x16x128_f8f6f4 v[142:145], v[2:9], v[192:199], v[142:145], v182, v182 op_sel_hi:[0,0,0]
	v_mfma_scale_f32_16x16x128_f8f6f4 v[134:137], v[2:9], v[200:207], v[134:137], v182, v182 op_sel_hi:[0,0,0]
	v_mfma_scale_f32_16x16x128_f8f6f4 v[126:129], v[2:9], v[208:215], v[126:129], v182, v182 op_sel_hi:[0,0,0]
	v_mfma_scale_f32_16x16x128_f8f6f4 v[146:149], v[10:17], v[172:179], v[146:149], v182, v182 op_sel_hi:[0,0,0]
	v_mfma_scale_f32_16x16x128_f8f6f4 v[138:141], v[10:17], v[192:199], v[138:141], v182, v182 op_sel_hi:[0,0,0]
	v_mfma_scale_f32_16x16x128_f8f6f4 v[130:133], v[10:17], v[200:207], v[130:133], v182, v182 op_sel_hi:[0,0,0]
	v_mfma_scale_f32_16x16x128_f8f6f4 v[122:125], v[10:17], v[208:215], v[122:125], v182, v182 op_sel_hi:[0,0,0]
	s_setprio 0
	s_setprio 1
	v_mfma_scale_f32_16x16x128_f8f6f4 v[118:121], v[18:25], v[172:179], v[118:121], v182, v182 op_sel_hi:[0,0,0]
	v_mfma_scale_f32_16x16x128_f8f6f4 v[110:113], v[18:25], v[192:199], v[110:113], v182, v182 op_sel_hi:[0,0,0]
	v_mfma_scale_f32_16x16x128_f8f6f4 v[102:105], v[18:25], v[200:207], v[102:105], v182, v182 op_sel_hi:[0,0,0]
	v_mfma_scale_f32_16x16x128_f8f6f4 v[94:97], v[18:25], v[208:215], v[94:97], v182, v182 op_sel_hi:[0,0,0]
	v_mfma_scale_f32_16x16x128_f8f6f4 v[114:117], v[184:191], v[172:179], v[114:117], v182, v182 op_sel_hi:[0,0,0]
	v_mfma_scale_f32_16x16x128_f8f6f4 v[106:109], v[184:191], v[192:199], v[106:109], v182, v182 op_sel_hi:[0,0,0]
	v_mfma_scale_f32_16x16x128_f8f6f4 v[98:101], v[184:191], v[200:207], v[98:101], v182, v182 op_sel_hi:[0,0,0]
	v_mfma_scale_f32_16x16x128_f8f6f4 v[90:93], v[184:191], v[208:215], v[90:93], v182, v182 op_sel_hi:[0,0,0]
	s_setprio 0
	s_barrier
	s_add_i32 s50, s46, s37
	v_lshl_add_u64 v[172:173], s[24:25], 0, v[160:161]
	s_mov_b32 m0, s50
	ds_read_b128 v[192:195], v181 offset:16384
	ds_read_b128 v[196:199], v181 offset:17408
	ds_read_b128 v[200:203], v181 offset:18432
	ds_read_b128 v[204:207], v181 offset:19456
	ds_read_b128 v[208:211], v181 offset:20480
	ds_read_b128 v[212:215], v181 offset:21504
	ds_read_b128 v[216:219], v181 offset:22528
	ds_read_b128 v[220:223], v181 offset:23552
	global_load_lds_dwordx4 v[172:173], off
	s_add_i32 m0, s50, 0x2000
	s_add_u32 s64, s24, 0x4000
	v_lshl_add_u64 v[174:175], s[24:25], 0, v[156:157]
	s_addc_u32 s65, s25, 0
	s_add_i32 s50, s47, s37
	global_load_lds_dwordx4 v[174:175], off
	v_lshl_add_u64 v[176:177], s[64:65], 0, v[160:161]
	s_mov_b32 m0, s50
	v_lshl_add_u64 v[178:179], s[26:27], 0, v[158:159]
	global_load_lds_dwordx4 v[176:177], off
	v_lshl_add_u64 v[176:177], s[64:65], 0, v[156:157]
	s_add_i32 m0, s50, 0x2000
	s_nop 0
	global_load_lds_dwordx4 v[176:177], off
	v_lshl_add_u64 v[176:177], s[26:27], 0, v[162:163]
	s_mov_b32 m0, s21
	s_nop 0
	global_load_lds_dwordx4 v[176:177], off
	s_mov_b32 m0, s40
	s_nop 0
	global_load_lds_dwordx4 v[178:179], off
	s_waitcnt vmcnt(8)
	s_waitcnt lgkmcnt(0)
	s_barrier
	s_setprio 1
	s_waitcnt lgkmcnt(0)
	v_mfma_scale_f32_16x16x128_f8f6f4 v[86:89], v[2:9], v[192:199], v[86:89], v182, v182 op_sel_hi:[0,0,0]
	v_mfma_scale_f32_16x16x128_f8f6f4 v[78:81], v[2:9], v[200:207], v[78:81], v182, v182 op_sel_hi:[0,0,0]
	v_mfma_scale_f32_16x16x128_f8f6f4 v[70:73], v[2:9], v[208:215], v[70:73], v182, v182 op_sel_hi:[0,0,0]
	v_mfma_scale_f32_16x16x128_f8f6f4 v[62:65], v[2:9], v[216:223], v[62:65], v182, v182 op_sel_hi:[0,0,0]
	v_mfma_scale_f32_16x16x128_f8f6f4 v[82:85], v[10:17], v[192:199], v[82:85], v182, v182 op_sel_hi:[0,0,0]
	v_mfma_scale_f32_16x16x128_f8f6f4 v[74:77], v[10:17], v[200:207], v[74:77], v182, v182 op_sel_hi:[0,0,0]
	v_mfma_scale_f32_16x16x128_f8f6f4 v[66:69], v[10:17], v[208:215], v[66:69], v182, v182 op_sel_hi:[0,0,0]
	v_mfma_scale_f32_16x16x128_f8f6f4 v[58:61], v[10:17], v[216:223], v[58:61], v182, v182 op_sel_hi:[0,0,0]
	s_setprio 0
	s_setprio 1
	v_mfma_scale_f32_16x16x128_f8f6f4 v[54:57], v[18:25], v[192:199], v[54:57], v182, v182 op_sel_hi:[0,0,0]
	v_mfma_scale_f32_16x16x128_f8f6f4 v[46:49], v[18:25], v[200:207], v[46:49], v182, v182 op_sel_hi:[0,0,0]
	v_mfma_scale_f32_16x16x128_f8f6f4 v[38:41], v[18:25], v[208:215], v[38:41], v182, v182 op_sel_hi:[0,0,0]
	v_mfma_scale_f32_16x16x128_f8f6f4 v[30:33], v[18:25], v[216:223], v[30:33], v182, v182 op_sel_hi:[0,0,0]
	v_mfma_scale_f32_16x16x128_f8f6f4 v[50:53], v[184:191], v[192:199], v[50:53], v182, v182 op_sel_hi:[0,0,0]
	v_mfma_scale_f32_16x16x128_f8f6f4 v[42:45], v[184:191], v[200:207], v[42:45], v182, v182 op_sel_hi:[0,0,0]
	v_mfma_scale_f32_16x16x128_f8f6f4 v[34:37], v[184:191], v[208:215], v[34:37], v182, v182 op_sel_hi:[0,0,0]
	v_mfma_scale_f32_16x16x128_f8f6f4 v[26:29], v[184:191], v[216:223], v[26:29], v182, v182 op_sel_hi:[0,0,0]
	s_setprio 0
	s_barrier
	s_add_i32 s63, 0, 0x18000
	s_add_i32 s50, 0, 0x1c000
	v_add_u32_e32 v2, s63, v180
	v_add_u32_e32 v22, s50, v180
	ds_read_b128 v[10:13], v2
	ds_read_b128 v[14:17], v2 offset:1024
	ds_read_b128 v[184:187], v2 offset:2048
	ds_read_b128 v[188:191], v2 offset:3072
	ds_read_b128 v[2:5], v22
	ds_read_b128 v[6:9], v22 offset:1024
	ds_read_b128 v[18:21], v22 offset:2048
	ds_read_b128 v[22:25], v22 offset:3072
	s_add_u32 s26, s26, 0x40000
	s_addc_u32 s27, s27, 0
	s_mov_b32 m0, s41
	v_lshl_add_u64 v[224:225], s[26:27], 0, v[162:163]
	ds_read_b128 v[192:195], v181 offset:32768
	ds_read_b128 v[196:199], v181 offset:33792
	ds_read_b128 v[200:203], v181 offset:34816
	ds_read_b128 v[204:207], v181 offset:35840
	ds_read_b128 v[208:211], v181 offset:36864
	ds_read_b128 v[212:215], v181 offset:37888
	ds_read_b128 v[216:219], v181 offset:38912
	ds_read_b128 v[220:223], v181 offset:39936
	global_load_lds_dwordx4 v[224:225], off
	v_lshl_add_u64 v[224:225], s[26:27], 0, v[158:159]
	s_mov_b32 m0, s42
	s_nop 0
	global_load_lds_dwordx4 v[224:225], off
	s_waitcnt vmcnt(8)
	s_waitcnt lgkmcnt(0)
	s_barrier
	s_setprio 1
	s_waitcnt lgkmcnt(0)
	v_mfma_scale_f32_16x16x128_f8f6f4 v[150:153], v[10:17], v[192:199], v[150:153], v182, v182 op_sel_hi:[0,0,0]
	v_mfma_scale_f32_16x16x128_f8f6f4 v[142:145], v[10:17], v[200:207], v[142:145], v182, v182 op_sel_hi:[0,0,0]
	v_mfma_scale_f32_16x16x128_f8f6f4 v[134:137], v[10:17], v[208:215], v[134:137], v182, v182 op_sel_hi:[0,0,0]
	v_mfma_scale_f32_16x16x128_f8f6f4 v[126:129], v[10:17], v[216:223], v[126:129], v182, v182 op_sel_hi:[0,0,0]
	v_mfma_scale_f32_16x16x128_f8f6f4 v[146:149], v[184:191], v[192:199], v[146:149], v182, v182 op_sel_hi:[0,0,0]
	v_mfma_scale_f32_16x16x128_f8f6f4 v[138:141], v[184:191], v[200:207], v[138:141], v182, v182 op_sel_hi:[0,0,0]
	v_mfma_scale_f32_16x16x128_f8f6f4 v[130:133], v[184:191], v[208:215], v[130:133], v182, v182 op_sel_hi:[0,0,0]
	v_mfma_scale_f32_16x16x128_f8f6f4 v[122:125], v[184:191], v[216:223], v[122:125], v182, v182 op_sel_hi:[0,0,0]
	s_setprio 0
	s_setprio 1
	v_mfma_scale_f32_16x16x128_f8f6f4 v[118:121], v[2:9], v[192:199], v[118:121], v182, v182 op_sel_hi:[0,0,0]
	v_mfma_scale_f32_16x16x128_f8f6f4 v[110:113], v[2:9], v[200:207], v[110:113], v182, v182 op_sel_hi:[0,0,0]
	v_mfma_scale_f32_16x16x128_f8f6f4 v[102:105], v[2:9], v[208:215], v[102:105], v182, v182 op_sel_hi:[0,0,0]
	v_mfma_scale_f32_16x16x128_f8f6f4 v[94:97], v[2:9], v[216:223], v[94:97], v182, v182 op_sel_hi:[0,0,0]
	v_mfma_scale_f32_16x16x128_f8f6f4 v[114:117], v[18:25], v[192:199], v[114:117], v182, v182 op_sel_hi:[0,0,0]
	v_mfma_scale_f32_16x16x128_f8f6f4 v[106:109], v[18:25], v[200:207], v[106:109], v182, v182 op_sel_hi:[0,0,0]
	v_mfma_scale_f32_16x16x128_f8f6f4 v[98:101], v[18:25], v[208:215], v[98:101], v182, v182 op_sel_hi:[0,0,0]
	v_mfma_scale_f32_16x16x128_f8f6f4 v[90:93], v[18:25], v[216:223], v[90:93], v182, v182 op_sel_hi:[0,0,0]
	s_setprio 0
	s_barrier
	s_add_i32 s26, s63, s37
	v_lshl_add_u64 v[172:173], v[172:173], 0, s[8:9]
	s_mov_b32 m0, s26
	ds_read_b128 v[192:195], v181 offset:49152
	ds_read_b128 v[196:199], v181 offset:50176
	ds_read_b128 v[200:203], v181 offset:51200
	ds_read_b128 v[204:207], v181 offset:52224
	ds_read_b128 v[208:211], v181 offset:53248
	ds_read_b128 v[212:215], v181 offset:54272
	ds_read_b128 v[216:219], v181 offset:55296
	ds_read_b128 v[220:223], v181 offset:56320
	global_load_lds_dwordx4 v[172:173], off
	s_add_i32 m0, s26, 0x2000
	s_add_u32 s24, s24, 0x4080
	v_lshl_add_u64 v[172:173], v[174:175], 0, s[8:9]
	s_addc_u32 s25, s25, 0
	s_add_i32 s26, s50, s37
	global_load_lds_dwordx4 v[172:173], off
	v_lshl_add_u64 v[172:173], s[24:25], 0, v[160:161]
	s_mov_b32 m0, s26
	s_nop 0
	global_load_lds_dwordx4 v[172:173], off
	v_lshl_add_u64 v[172:173], s[24:25], 0, v[156:157]
	s_add_i32 m0, s26, 0x2000
	s_nop 0
	global_load_lds_dwordx4 v[172:173], off
	v_lshl_add_u64 v[172:173], v[176:177], 0, s[8:9]
	s_mov_b32 m0, s43
	s_nop 0
	global_load_lds_dwordx4 v[172:173], off
	v_lshl_add_u64 v[172:173], v[178:179], 0, s[8:9]
	s_mov_b32 m0, s44
	s_nop 0
	global_load_lds_dwordx4 v[172:173], off
	s_waitcnt vmcnt(8)
	s_waitcnt lgkmcnt(0)
	s_barrier
	s_setprio 1
	s_waitcnt lgkmcnt(0)
	v_mfma_scale_f32_16x16x128_f8f6f4 v[86:89], v[10:17], v[192:199], v[86:89], v182, v182 op_sel_hi:[0,0,0]
	v_mfma_scale_f32_16x16x128_f8f6f4 v[78:81], v[10:17], v[200:207], v[78:81], v182, v182 op_sel_hi:[0,0,0]
	v_mfma_scale_f32_16x16x128_f8f6f4 v[70:73], v[10:17], v[208:215], v[70:73], v182, v182 op_sel_hi:[0,0,0]
	v_mfma_scale_f32_16x16x128_f8f6f4 v[62:65], v[10:17], v[216:223], v[62:65], v182, v182 op_sel_hi:[0,0,0]
	v_mfma_scale_f32_16x16x128_f8f6f4 v[82:85], v[184:191], v[192:199], v[82:85], v182, v182 op_sel_hi:[0,0,0]
	v_mfma_scale_f32_16x16x128_f8f6f4 v[74:77], v[184:191], v[200:207], v[74:77], v182, v182 op_sel_hi:[0,0,0]
	v_mfma_scale_f32_16x16x128_f8f6f4 v[66:69], v[184:191], v[208:215], v[66:69], v182, v182 op_sel_hi:[0,0,0]
	v_mfma_scale_f32_16x16x128_f8f6f4 v[58:61], v[184:191], v[216:223], v[58:61], v182, v182 op_sel_hi:[0,0,0]
	s_setprio 0
	s_setprio 1
	v_mfma_scale_f32_16x16x128_f8f6f4 v[54:57], v[2:9], v[192:199], v[54:57], v182, v182 op_sel_hi:[0,0,0]
	v_mfma_scale_f32_16x16x128_f8f6f4 v[46:49], v[2:9], v[200:207], v[46:49], v182, v182 op_sel_hi:[0,0,0]
	v_mfma_scale_f32_16x16x128_f8f6f4 v[38:41], v[2:9], v[208:215], v[38:41], v182, v182 op_sel_hi:[0,0,0]
	v_mfma_scale_f32_16x16x128_f8f6f4 v[30:33], v[2:9], v[216:223], v[30:33], v182, v182 op_sel_hi:[0,0,0]
	v_mfma_scale_f32_16x16x128_f8f6f4 v[50:53], v[18:25], v[192:199], v[50:53], v182, v182 op_sel_hi:[0,0,0]
	v_mfma_scale_f32_16x16x128_f8f6f4 v[42:45], v[18:25], v[200:207], v[42:45], v182, v182 op_sel_hi:[0,0,0]
	v_mfma_scale_f32_16x16x128_f8f6f4 v[34:37], v[18:25], v[208:215], v[34:37], v182, v182 op_sel_hi:[0,0,0]
	v_mfma_scale_f32_16x16x128_f8f6f4 v[26:29], v[18:25], v[216:223], v[26:29], v182, v182 op_sel_hi:[0,0,0]
	s_setprio 0
	s_barrier
	s_add_i32 s62, s62, 2
	s_add_u32 s22, s22, 0x100
	s_addc_u32 s23, s23, 0
	s_add_u32 s60, s60, 0x100
	s_addc_u32 s61, s61, 0
	s_cmp_gt_u32 s62, 13
	s_cbranch_scc0 .LBB0_739
	s_and_b64 vcc, exec, s[10:11]
	s_cbranch_vccz .LBB0_742
	s_barrier

.LBB0_839:
	v_add_u32_e32 v14, s48, v178
	v_add_u32_e32 v170, s49, v178
	ds_read_b128 v[2:5], v14
	ds_read_b128 v[6:9], v14 offset:1024
	ds_read_b128 v[10:13], v14 offset:2048
	ds_read_b128 v[14:17], v14 offset:3072
	ds_read_b128 v[18:21], v170
	ds_read_b128 v[22:25], v170 offset:1024
	ds_read_b128 v[184:187], v170 offset:2048
	ds_read_b128 v[188:191], v170 offset:3072
	s_add_i32 s65, s24, 2
	s_add_u32 s25, s22, 0xfff00080
	s_addc_u32 s26, s23, -1
	s_cmp_eq_u32 s13, s24
	s_cselect_b32 s24, s20, s15
	s_cselect_b32 s27, s19, s26
	s_cselect_b32 s26, s18, s25
	s_cselect_b32 s25, s21, s64
	v_lshl_add_u64 v[216:217], s[22:23], 0, v[162:163]
	s_add_i32 m0, s17, 0xc000
	ds_read_b128 v[170:173], v181
	ds_read_b128 v[174:177], v181 offset:1024
	ds_read_b128 v[192:195], v181 offset:2048
	ds_read_b128 v[196:199], v181 offset:3072
	ds_read_b128 v[200:203], v181 offset:4096
	ds_read_b128 v[204:207], v181 offset:5120
	ds_read_b128 v[208:211], v181 offset:6144
	ds_read_b128 v[212:215], v181 offset:7168
	global_load_lds_dwordx4 v[216:217], off
	v_lshl_add_u64 v[216:217], s[22:23], 0, v[164:165]
	s_add_i32 m0, s17, 0xe000
	s_nop 0
	global_load_lds_dwordx4 v[216:217], off
	s_waitcnt vmcnt(8)
	s_waitcnt lgkmcnt(0)
	s_barrier
	s_setprio 1
	s_waitcnt lgkmcnt(0)
	v_mfma_scale_f32_16x16x128_f8f6f4 v[150:153], v[2:9], v[170:177], v[150:153], v182, v182 op_sel_hi:[0,0,0]
	v_mfma_scale_f32_16x16x128_f8f6f4 v[142:145], v[2:9], v[192:199], v[142:145], v182, v182 op_sel_hi:[0,0,0]
	v_mfma_scale_f32_16x16x128_f8f6f4 v[134:137], v[2:9], v[200:207], v[134:137], v182, v182 op_sel_hi:[0,0,0]
	v_mfma_scale_f32_16x16x128_f8f6f4 v[126:129], v[2:9], v[208:215], v[126:129], v182, v182 op_sel_hi:[0,0,0]
	v_mfma_scale_f32_16x16x128_f8f6f4 v[146:149], v[10:17], v[170:177], v[146:149], v182, v182 op_sel_hi:[0,0,0]
	v_mfma_scale_f32_16x16x128_f8f6f4 v[138:141], v[10:17], v[192:199], v[138:141], v182, v182 op_sel_hi:[0,0,0]
	v_mfma_scale_f32_16x16x128_f8f6f4 v[130:133], v[10:17], v[200:207], v[130:133], v182, v182 op_sel_hi:[0,0,0]
	v_mfma_scale_f32_16x16x128_f8f6f4 v[122:125], v[10:17], v[208:215], v[122:125], v182, v182 op_sel_hi:[0,0,0]
	s_setprio 0
	s_setprio 1
	v_mfma_scale_f32_16x16x128_f8f6f4 v[118:121], v[18:25], v[170:177], v[118:121], v182, v182 op_sel_hi:[0,0,0]
	v_mfma_scale_f32_16x16x128_f8f6f4 v[110:113], v[18:25], v[192:199], v[110:113], v182, v182 op_sel_hi:[0,0,0]
	v_mfma_scale_f32_16x16x128_f8f6f4 v[102:105], v[18:25], v[200:207], v[102:105], v182, v182 op_sel_hi:[0,0,0]
	v_mfma_scale_f32_16x16x128_f8f6f4 v[94:97], v[18:25], v[208:215], v[94:97], v182, v182 op_sel_hi:[0,0,0]
	v_mfma_scale_f32_16x16x128_f8f6f4 v[114:117], v[184:191], v[170:177], v[114:117], v182, v182 op_sel_hi:[0,0,0]
	v_mfma_scale_f32_16x16x128_f8f6f4 v[106:109], v[184:191], v[192:199], v[106:109], v182, v182 op_sel_hi:[0,0,0]
	v_mfma_scale_f32_16x16x128_f8f6f4 v[98:101], v[184:191], v[200:207], v[98:101], v182, v182 op_sel_hi:[0,0,0]
	v_mfma_scale_f32_16x16x128_f8f6f4 v[90:93], v[184:191], v[208:215], v[90:93], v182, v182 op_sel_hi:[0,0,0]
	s_setprio 0
	s_barrier
	s_add_i32 s50, s48, s29
	v_lshl_add_u64 v[170:171], s[24:25], 0, v[156:157]
	s_mov_b32 m0, s50
	ds_read_b128 v[192:195], v181 offset:16384
	ds_read_b128 v[196:199], v181 offset:17408
	ds_read_b128 v[200:203], v181 offset:18432
	ds_read_b128 v[204:207], v181 offset:19456
	ds_read_b128 v[208:211], v181 offset:20480
	ds_read_b128 v[212:215], v181 offset:21504
	ds_read_b128 v[216:219], v181 offset:22528
	ds_read_b128 v[220:223], v181 offset:23552
	global_load_lds_dwordx4 v[170:171], off
	s_add_i32 m0, s50, 0x2000
	s_add_u32 s66, s24, 0x100000
	v_lshl_add_u64 v[172:173], s[24:25], 0, v[160:161]
	s_addc_u32 s67, s25, 0
	s_add_i32 s50, s49, s29
	global_load_lds_dwordx4 v[172:173], off
	v_lshl_add_u64 v[174:175], s[66:67], 0, v[156:157]
	s_mov_b32 m0, s50
	v_lshl_add_u64 v[176:177], s[26:27], 0, v[158:159]
	global_load_lds_dwordx4 v[174:175], off
	v_lshl_add_u64 v[174:175], s[66:67], 0, v[160:161]
	s_add_i32 m0, s50, 0x2000
	s_nop 0
	global_load_lds_dwordx4 v[174:175], off
	v_lshl_add_u64 v[174:175], s[26:27], 0, v[154:155]
	s_mov_b32 m0, s17
	s_nop 0
	global_load_lds_dwordx4 v[174:175], off
	s_mov_b32 m0, s39
	s_nop 0
	global_load_lds_dwordx4 v[176:177], off
	s_waitcnt vmcnt(8)
	s_waitcnt lgkmcnt(0)
	s_barrier
	s_setprio 1
	s_waitcnt lgkmcnt(0)
	v_mfma_scale_f32_16x16x128_f8f6f4 v[86:89], v[2:9], v[192:199], v[86:89], v182, v182 op_sel_hi:[0,0,0]
	v_mfma_scale_f32_16x16x128_f8f6f4 v[78:81], v[2:9], v[200:207], v[78:81], v182, v182 op_sel_hi:[0,0,0]
	v_mfma_scale_f32_16x16x128_f8f6f4 v[70:73], v[2:9], v[208:215], v[70:73], v182, v182 op_sel_hi:[0,0,0]
	v_mfma_scale_f32_16x16x128_f8f6f4 v[62:65], v[2:9], v[216:223], v[62:65], v182, v182 op_sel_hi:[0,0,0]
	v_mfma_scale_f32_16x16x128_f8f6f4 v[82:85], v[10:17], v[192:199], v[82:85], v182, v182 op_sel_hi:[0,0,0]
	v_mfma_scale_f32_16x16x128_f8f6f4 v[74:77], v[10:17], v[200:207], v[74:77], v182, v182 op_sel_hi:[0,0,0]
	v_mfma_scale_f32_16x16x128_f8f6f4 v[66:69], v[10:17], v[208:215], v[66:69], v182, v182 op_sel_hi:[0,0,0]
	v_mfma_scale_f32_16x16x128_f8f6f4 v[58:61], v[10:17], v[216:223], v[58:61], v182, v182 op_sel_hi:[0,0,0]
	s_setprio 0
	s_setprio 1
	v_mfma_scale_f32_16x16x128_f8f6f4 v[54:57], v[18:25], v[192:199], v[54:57], v182, v182 op_sel_hi:[0,0,0]
	v_mfma_scale_f32_16x16x128_f8f6f4 v[46:49], v[18:25], v[200:207], v[46:49], v182, v182 op_sel_hi:[0,0,0]
	v_mfma_scale_f32_16x16x128_f8f6f4 v[38:41], v[18:25], v[208:215], v[38:41], v182, v182 op_sel_hi:[0,0,0]
	v_mfma_scale_f32_16x16x128_f8f6f4 v[30:33], v[18:25], v[216:223], v[30:33], v182, v182 op_sel_hi:[0,0,0]
	v_mfma_scale_f32_16x16x128_f8f6f4 v[50:53], v[184:191], v[192:199], v[50:53], v182, v182 op_sel_hi:[0,0,0]
	v_mfma_scale_f32_16x16x128_f8f6f4 v[42:45], v[184:191], v[200:207], v[42:45], v182, v182 op_sel_hi:[0,0,0]
	v_mfma_scale_f32_16x16x128_f8f6f4 v[34:37], v[184:191], v[208:215], v[34:37], v182, v182 op_sel_hi:[0,0,0]
	v_mfma_scale_f32_16x16x128_f8f6f4 v[26:29], v[184:191], v[216:223], v[26:29], v182, v182 op_sel_hi:[0,0,0]
	s_setprio 0
	s_barrier
	s_add_i32 s66, 0, 0x18000
	s_add_i32 s50, 0, 0x1c000
	v_add_u32_e32 v2, s66, v178
	v_add_u32_e32 v22, s50, v178
	ds_read_b128 v[10:13], v2
	ds_read_b128 v[14:17], v2 offset:1024
	ds_read_b128 v[184:187], v2 offset:2048
	ds_read_b128 v[188:191], v2 offset:3072
	ds_read_b128 v[2:5], v22
	ds_read_b128 v[6:9], v22 offset:1024
	ds_read_b128 v[18:21], v22 offset:2048
	ds_read_b128 v[22:25], v22 offset:3072
	s_add_u32 s26, s26, 0x100000
	s_addc_u32 s27, s27, 0
	s_mov_b32 m0, s40
	v_lshl_add_u64 v[224:225], s[26:27], 0, v[154:155]
	ds_read_b128 v[192:195], v181 offset:32768
	ds_read_b128 v[196:199], v181 offset:33792
	ds_read_b128 v[200:203], v181 offset:34816
	ds_read_b128 v[204:207], v181 offset:35840
	ds_read_b128 v[208:211], v181 offset:36864
	ds_read_b128 v[212:215], v181 offset:37888
	ds_read_b128 v[216:219], v181 offset:38912
	ds_read_b128 v[220:223], v181 offset:39936
	global_load_lds_dwordx4 v[224:225], off
	v_lshl_add_u64 v[224:225], s[26:27], 0, v[158:159]
	s_mov_b32 m0, s41
	s_nop 0
	global_load_lds_dwordx4 v[224:225], off
	s_waitcnt vmcnt(8)
	s_waitcnt lgkmcnt(0)
	s_barrier
	s_setprio 1
	s_waitcnt lgkmcnt(0)
	v_mfma_scale_f32_16x16x128_f8f6f4 v[150:153], v[10:17], v[192:199], v[150:153], v182, v182 op_sel_hi:[0,0,0]
	v_mfma_scale_f32_16x16x128_f8f6f4 v[142:145], v[10:17], v[200:207], v[142:145], v182, v182 op_sel_hi:[0,0,0]
	v_mfma_scale_f32_16x16x128_f8f6f4 v[134:137], v[10:17], v[208:215], v[134:137], v182, v182 op_sel_hi:[0,0,0]
	v_mfma_scale_f32_16x16x128_f8f6f4 v[126:129], v[10:17], v[216:223], v[126:129], v182, v182 op_sel_hi:[0,0,0]
	v_mfma_scale_f32_16x16x128_f8f6f4 v[146:149], v[184:191], v[192:199], v[146:149], v182, v182 op_sel_hi:[0,0,0]
	v_mfma_scale_f32_16x16x128_f8f6f4 v[138:141], v[184:191], v[200:207], v[138:141], v182, v182 op_sel_hi:[0,0,0]
	v_mfma_scale_f32_16x16x128_f8f6f4 v[130:133], v[184:191], v[208:215], v[130:133], v182, v182 op_sel_hi:[0,0,0]
	v_mfma_scale_f32_16x16x128_f8f6f4 v[122:125], v[184:191], v[216:223], v[122:125], v182, v182 op_sel_hi:[0,0,0]
	s_setprio 0
	s_setprio 1
	v_mfma_scale_f32_16x16x128_f8f6f4 v[118:121], v[2:9], v[192:199], v[118:121], v182, v182 op_sel_hi:[0,0,0]
	v_mfma_scale_f32_16x16x128_f8f6f4 v[110:113], v[2:9], v[200:207], v[110:113], v182, v182 op_sel_hi:[0,0,0]
	v_mfma_scale_f32_16x16x128_f8f6f4 v[102:105], v[2:9], v[208:215], v[102:105], v182, v182 op_sel_hi:[0,0,0]
	v_mfma_scale_f32_16x16x128_f8f6f4 v[94:97], v[2:9], v[216:223], v[94:97], v182, v182 op_sel_hi:[0,0,0]
	v_mfma_scale_f32_16x16x128_f8f6f4 v[114:117], v[18:25], v[192:199], v[114:117], v182, v182 op_sel_hi:[0,0,0]
	v_mfma_scale_f32_16x16x128_f8f6f4 v[106:109], v[18:25], v[200:207], v[106:109], v182, v182 op_sel_hi:[0,0,0]
	v_mfma_scale_f32_16x16x128_f8f6f4 v[98:101], v[18:25], v[208:215], v[98:101], v182, v182 op_sel_hi:[0,0,0]
	v_mfma_scale_f32_16x16x128_f8f6f4 v[90:93], v[18:25], v[216:223], v[90:93], v182, v182 op_sel_hi:[0,0,0]
	s_setprio 0
	s_barrier
	s_add_i32 s26, s66, s29
	v_lshl_add_u64 v[170:171], v[170:171], 0, s[8:9]
	s_mov_b32 m0, s26
	ds_read_b128 v[192:195], v181 offset:49152
	ds_read_b128 v[196:199], v181 offset:50176
	ds_read_b128 v[200:203], v181 offset:51200
	ds_read_b128 v[204:207], v181 offset:52224
	ds_read_b128 v[208:211], v181 offset:53248
	ds_read_b128 v[212:215], v181 offset:54272
	ds_read_b128 v[216:219], v181 offset:55296
	ds_read_b128 v[220:223], v181 offset:56320
	global_load_lds_dwordx4 v[170:171], off
	s_add_i32 m0, s26, 0x2000
	s_add_u32 s24, s24, 0x100080
	v_lshl_add_u64 v[170:171], v[172:173], 0, s[8:9]
	s_addc_u32 s25, s25, 0
	s_add_i32 s26, s50, s29
	global_load_lds_dwordx4 v[170:171], off
	v_lshl_add_u64 v[170:171], s[24:25], 0, v[156:157]
	s_mov_b32 m0, s26
	s_nop 0
	global_load_lds_dwordx4 v[170:171], off
	v_lshl_add_u64 v[170:171], s[24:25], 0, v[160:161]
	s_add_i32 m0, s26, 0x2000
	s_nop 0
	global_load_lds_dwordx4 v[170:171], off
	v_lshl_add_u64 v[170:171], v[174:175], 0, s[8:9]
	s_mov_b32 m0, s43
	s_nop 0
	global_load_lds_dwordx4 v[170:171], off
	v_lshl_add_u64 v[170:171], v[176:177], 0, s[8:9]
	s_mov_b32 m0, s44
	s_nop 0
	global_load_lds_dwordx4 v[170:171], off
	s_waitcnt vmcnt(8)
	s_waitcnt lgkmcnt(0)
	s_barrier
	s_setprio 1
	s_waitcnt lgkmcnt(0)
	v_mfma_scale_f32_16x16x128_f8f6f4 v[86:89], v[10:17], v[192:199], v[86:89], v182, v182 op_sel_hi:[0,0,0]
	v_mfma_scale_f32_16x16x128_f8f6f4 v[78:81], v[10:17], v[200:207], v[78:81], v182, v182 op_sel_hi:[0,0,0]
	v_mfma_scale_f32_16x16x128_f8f6f4 v[70:73], v[10:17], v[208:215], v[70:73], v182, v182 op_sel_hi:[0,0,0]
	v_mfma_scale_f32_16x16x128_f8f6f4 v[62:65], v[10:17], v[216:223], v[62:65], v182, v182 op_sel_hi:[0,0,0]
	v_mfma_scale_f32_16x16x128_f8f6f4 v[82:85], v[184:191], v[192:199], v[82:85], v182, v182 op_sel_hi:[0,0,0]
	v_mfma_scale_f32_16x16x128_f8f6f4 v[74:77], v[184:191], v[200:207], v[74:77], v182, v182 op_sel_hi:[0,0,0]
	v_mfma_scale_f32_16x16x128_f8f6f4 v[66:69], v[184:191], v[208:215], v[66:69], v182, v182 op_sel_hi:[0,0,0]
	v_mfma_scale_f32_16x16x128_f8f6f4 v[58:61], v[184:191], v[216:223], v[58:61], v182, v182 op_sel_hi:[0,0,0]
	s_setprio 0
	s_setprio 1
	v_mfma_scale_f32_16x16x128_f8f6f4 v[54:57], v[2:9], v[192:199], v[54:57], v182, v182 op_sel_hi:[0,0,0]
	v_mfma_scale_f32_16x16x128_f8f6f4 v[46:49], v[2:9], v[200:207], v[46:49], v182, v182 op_sel_hi:[0,0,0]
	v_mfma_scale_f32_16x16x128_f8f6f4 v[38:41], v[2:9], v[208:215], v[38:41], v182, v182 op_sel_hi:[0,0,0]
	v_mfma_scale_f32_16x16x128_f8f6f4 v[30:33], v[2:9], v[216:223], v[30:33], v182, v182 op_sel_hi:[0,0,0]
	v_mfma_scale_f32_16x16x128_f8f6f4 v[50:53], v[18:25], v[192:199], v[50:53], v182, v182 op_sel_hi:[0,0,0]
	v_mfma_scale_f32_16x16x128_f8f6f4 v[42:45], v[18:25], v[200:207], v[42:45], v182, v182 op_sel_hi:[0,0,0]
	v_mfma_scale_f32_16x16x128_f8f6f4 v[34:37], v[18:25], v[208:215], v[34:37], v182, v182 op_sel_hi:[0,0,0]
	v_mfma_scale_f32_16x16x128_f8f6f4 v[26:29], v[18:25], v[216:223], v[26:29], v182, v182 op_sel_hi:[0,0,0]
	s_setprio 0
	s_barrier
	s_add_u32 s22, s22, 0x100
	s_addc_u32 s23, s23, 0
	s_add_u32 s15, s15, 0x100
	s_addc_u32 s64, s64, 0
	s_cmp_ge_i32 s65, s58
	s_mov_b32 s24, s65
	s_cbranch_scc0 .LBB0_839
